# attention: PV MFMAs interleaved with exp2/row-sum/pack of later P chunks (only the first chunk prepared before the first MFMA)
# speedup vs baseline: 1.0109x; 1.0109x over previous
.LBB0_509:
	v_exp_f32_e32 v82, v82
	v_exp_f32_e32 v83, v83
	v_exp_f32_e32 v84, v84
	v_exp_f32_e32 v85, v85
	v_exp_f32_e32 v86, v86
	v_exp_f32_e32 v87, v87
	v_exp_f32_e32 v88, v88
	v_exp_f32_e32 v89, v89
	s_waitcnt lgkmcnt(0)
	v_cvt_pk_bf16_f32 v174, v82, v83
	v_cvt_pk_bf16_f32 v175, v84, v85
	v_cvt_pk_bf16_f32 v176, v86, v87
	v_cvt_pk_bf16_f32 v177, v88, v89
	v_add_f32_e32 v190, v82, v83
	v_add_f32_e32 v191, v84, v85
	v_add_f32_e32 v192, v86, v87
	v_add_f32_e32 v193, v88, v89
	v_mfma_f32_32x32x16_bf16 v[50:65], v[126:129], v[174:177], v[50:65]
	v_exp_f32_e32 v90, v90
	v_exp_f32_e32 v91, v91
	v_add_f32_e32 v190, v190, v191
	v_add_f32_e32 v192, v192, v193
	v_mfma_f32_32x32x16_bf16 v[34:49], v[122:125], v[174:177], v[34:49]
	v_exp_f32_e32 v92, v92
	v_exp_f32_e32 v93, v93
	v_cvt_pk_bf16_f32 v178, v90, v91
	v_add_f32_e32 v191, v90, v91
	v_mfma_f32_32x32x16_bf16 v[18:33], v[118:121], v[174:177], v[18:33]
	v_exp_f32_e32 v94, v94
	v_exp_f32_e32 v95, v95
	v_cvt_pk_bf16_f32 v179, v92, v93
	v_add_f32_e32 v193, v92, v93
	v_mfma_f32_32x32x16_bf16 v[2:17], v[114:117], v[174:177], v[2:17]
	v_exp_f32_e32 v96, v96
	v_exp_f32_e32 v97, v97
	v_cvt_pk_bf16_f32 v180, v94, v95
	v_add_f32_e32 v190, v190, v191
	v_add_f32_e32 v191, v94, v95
	v_cvt_pk_bf16_f32 v181, v96, v97
	v_add_f32_e32 v192, v192, v193
	v_add_f32_e32 v193, v96, v97
	v_mfma_f32_32x32x16_bf16 v[50:65], v[110:113], v[178:181], v[50:65]
	v_xor_b32_e32 v172, 64, v156
	v_xor_b32_e32 v0, 0x60, v156
	ds_read_b128 v[82:85], v172
	ds_read_b128 v[86:89], v172 offset:4096
	ds_read_b128 v[90:93], v172 offset:8192
	ds_read_b128 v[94:97], v172 offset:12288
	v_exp_f32_e32 v66, v66
	v_exp_f32_e32 v67, v67
	v_mfma_f32_32x32x16_bf16 v[34:49], v[106:109], v[178:181], v[34:49]
	ds_read_b128 v[156:159], v0
	ds_read_b128 v[160:163], v0 offset:4096
	ds_read_b128 v[164:167], v0 offset:8192
	ds_read_b128 v[168:171], v0 offset:12288
	v_exp_f32_e32 v68, v68
	v_exp_f32_e32 v69, v69
	v_cvt_pk_bf16_f32 v182, v66, v67
	v_add_f32_e32 v190, v190, v191
	v_mfma_f32_32x32x16_bf16 v[18:33], v[102:105], v[178:181], v[18:33]
	v_exp_f32_e32 v70, v70
	v_exp_f32_e32 v71, v71
	v_cvt_pk_bf16_f32 v183, v68, v69
	v_add_f32_e32 v191, v66, v67
	v_add_f32_e32 v192, v192, v193
	v_mfma_f32_32x32x16_bf16 v[2:17], v[98:101], v[178:181], v[2:17]
	v_exp_f32_e32 v72, v72
	v_exp_f32_e32 v73, v73
	v_cvt_pk_bf16_f32 v184, v70, v71
	v_add_f32_e32 v193, v68, v69
	v_add_f32_e32 v190, v190, v191
	v_cvt_pk_bf16_f32 v185, v72, v73
	v_add_f32_e32 v191, v70, v71
	s_waitcnt lgkmcnt(0)
	v_mfma_f32_32x32x16_bf16 v[50:65], v[82:85], v[182:185], v[50:65]
	v_exp_f32_e32 v74, v74
	v_exp_f32_e32 v75, v75
	v_add_f32_e32 v192, v192, v193
	v_add_f32_e32 v193, v72, v73
	v_mfma_f32_32x32x16_bf16 v[34:49], v[86:89], v[182:185], v[34:49]
	v_exp_f32_e32 v76, v76
	v_exp_f32_e32 v77, v77
	v_cvt_pk_bf16_f32 v186, v74, v75
	v_add_f32_e32 v190, v190, v191
	v_mfma_f32_32x32x16_bf16 v[18:33], v[90:93], v[182:185], v[18:33]
	v_exp_f32_e32 v78, v78
	v_exp_f32_e32 v79, v79
	v_cvt_pk_bf16_f32 v187, v76, v77
	v_add_f32_e32 v191, v74, v75
	v_add_f32_e32 v192, v192, v193
	v_mfma_f32_32x32x16_bf16 v[2:17], v[94:97], v[182:185], v[2:17]
	v_exp_f32_e32 v80, v80
	v_exp_f32_e32 v81, v81
	v_cvt_pk_bf16_f32 v188, v78, v79
	v_add_f32_e32 v193, v76, v77
	v_add_f32_e32 v190, v190, v191
	v_cvt_pk_bf16_f32 v189, v80, v81
	v_add_f32_e32 v191, v78, v79
	v_add_f32_e32 v192, v192, v193
	v_mfma_f32_32x32x16_bf16 v[50:65], v[156:159], v[186:189], v[50:65]
	v_add_f32_e32 v193, v80, v81
	v_add_f32_e32 v190, v190, v191
	v_mfma_f32_32x32x16_bf16 v[34:49], v[160:163], v[186:189], v[34:49]
	v_add_f32_e32 v192, v192, v193
	v_mfma_f32_32x32x16_bf16 v[18:33], v[164:167], v[186:189], v[18:33]
	v_add_f32_e32 v190, v190, v192
	v_mfma_f32_32x32x16_bf16 v[2:17], v[168:171], v[186:189], v[2:17]
	v_add_f32_e32 v155, v155, v190
